# three partial-sum barriers: phase stores made write-through (sc1), XCD leader's L2 write-back dropped there
# baseline (speedup 1.0000x reference)
.LBB0_771:
	s_ashr_i32 s19, s18, 6
	s_bfe_u32 s20, s18, 0x20004
	s_lshl_b32 s4, s19, 8
	s_lshl_b32 s5, s20, 5
	s_or_b32 s8, s5, s4
	s_and_b32 s6, s3, 0x1e0
	s_ashr_i32 s9, s8, 31
	s_lshl_b64 s[4:5], s[8:9], 11
	s_or_b32 s9, s6, 0x4000
	s_lshl_b32 s6, s9, 11
	s_waitcnt vmcnt(33)
	v_lshl_add_u64 v[72:73], v[2:3], 0, s[6:7]
	v_lshl_add_u64 v[70:71], v[4:5], 0, s[4:5]
	v_add_co_u32_e64 v74, s[4:5], s15, v72
	s_waitcnt lgkmcnt(0)
	global_load_dwordx4 v[10:13], v[70:71], off
	v_addc_co_u32_e64 v75, s[4:5], 0, v73, s[4:5]
	v_add_co_u32_e64 v76, s[4:5], s15, v70
	global_load_dwordx4 v[14:17], v[72:73], off
	s_waitcnt vmcnt(34)
	v_addc_co_u32_e64 v77, s[4:5], 0, v71, s[4:5]
	v_add_co_u32_e64 v78, s[4:5], s16, v70
	global_load_dwordx4 v[18:21], v[72:73], off offset:64
	global_load_dwordx4 v[22:25], v[74:75], off
	v_addc_co_u32_e64 v79, s[4:5], 0, v71, s[4:5]
	v_add_co_u32_e64 v80, s[4:5], s17, v70
	global_load_dwordx4 v[26:29], v[70:71], off offset:64
	s_nop 0
	v_addc_co_u32_e64 v81, s[4:5], 0, v71, s[4:5]
	global_load_dwordx4 v[34:37], v[76:77], off
	global_load_dwordx4 v[38:41], v[74:75], off offset:64
	global_load_dwordx4 v[42:45], v[76:77], off offset:64
	global_load_dwordx4 v[50:53], v[78:79], off
	global_load_dwordx4 v[54:57], v[78:79], off offset:64
	global_load_dwordx4 v[62:65], v[80:81], off
	global_load_dwordx4 v[66:69], v[80:81], off offset:64
	s_waitcnt vmcnt(10)
	v_mfma_f32_16x16x32_bf16 v[30:33], v[10:13], v[14:17], 0
	s_waitcnt vmcnt(8)
	v_mfma_f32_16x16x32_bf16 v[10:13], v[10:13], v[22:25], 0
	s_waitcnt vmcnt(6)
	v_mfma_f32_16x16x32_bf16 v[46:49], v[34:37], v[14:17], 0
	v_mfma_f32_16x16x32_bf16 v[34:37], v[34:37], v[22:25], 0
	s_waitcnt vmcnt(3)
	v_mfma_f32_16x16x32_bf16 v[58:61], v[50:53], v[14:17], 0
	s_waitcnt vmcnt(1)
	v_mfma_f32_16x16x32_bf16 v[14:17], v[62:65], v[14:17], 0
	v_mfma_f32_16x16x32_bf16 v[30:33], v[26:29], v[18:21], v[30:33]
	v_mfma_f32_16x16x32_bf16 v[10:13], v[26:29], v[38:41], v[10:13]
	v_mfma_f32_16x16x32_bf16 v[26:29], v[42:45], v[18:21], v[46:49]
	v_mfma_f32_16x16x32_bf16 v[34:37], v[42:45], v[38:41], v[34:37]
	v_mfma_f32_16x16x32_bf16 v[42:45], v[54:57], v[18:21], v[58:61]
	s_waitcnt vmcnt(0)
	v_mfma_f32_16x16x32_bf16 v[14:17], v[66:69], v[18:21], v[14:17]
	global_load_dwordx4 v[18:21], v[70:71], off offset:128
	v_mfma_f32_16x16x32_bf16 v[50:53], v[50:53], v[22:25], 0
	v_mfma_f32_16x16x32_bf16 v[22:25], v[62:65], v[22:25], 0
	v_mfma_f32_16x16x32_bf16 v[46:49], v[54:57], v[38:41], v[50:53]
	v_mfma_f32_16x16x32_bf16 v[22:25], v[66:69], v[38:41], v[22:25]
	global_load_dwordx4 v[38:41], v[72:73], off offset:128
	s_nop 3
	global_load_dwordx4 v[50:53], v[72:73], off offset:192
	global_load_dwordx4 v[54:57], v[70:71], off offset:192
	global_load_dwordx4 v[58:61], v[74:75], off offset:128
	global_load_dwordx4 v[62:65], v[74:75], off offset:192
	s_waitcnt vmcnt(4)
	v_mfma_f32_16x16x32_bf16 v[30:33], v[18:21], v[38:41], v[30:33]
	s_waitcnt vmcnt(1)
	v_mfma_f32_16x16x32_bf16 v[10:13], v[18:21], v[58:61], v[10:13]
	global_load_dwordx4 v[18:21], v[76:77], off offset:128
	global_load_dwordx4 v[66:69], v[76:77], off offset:192
	v_mfma_f32_16x16x32_bf16 v[30:33], v[54:57], v[50:53], v[30:33]
	s_waitcnt vmcnt(2)
	v_mfma_f32_16x16x32_bf16 v[10:13], v[54:57], v[62:65], v[10:13]
	s_waitcnt vmcnt(1)
	v_mfma_f32_16x16x32_bf16 v[26:29], v[18:21], v[38:41], v[26:29]
	v_mfma_f32_16x16x32_bf16 v[18:21], v[18:21], v[58:61], v[34:37]
	s_nop 2
	global_load_dwordx4 v[34:37], v[78:79], off offset:128
	global_load_dwordx4 v[70:73], v[78:79], off offset:192
	global_load_dwordx4 v[74:77], v[80:81], off offset:128
	s_waitcnt vmcnt(3)
	v_mfma_f32_16x16x32_bf16 v[26:29], v[66:69], v[50:53], v[26:29]
	s_waitcnt vmcnt(2)
	v_mfma_f32_16x16x32_bf16 v[42:45], v[34:37], v[38:41], v[42:45]
	v_mfma_f32_16x16x32_bf16 v[34:37], v[34:37], v[58:61], v[46:49]
	s_nop 2
	global_load_dwordx4 v[46:49], v[80:81], off offset:192
	s_waitcnt vmcnt(1)
	v_mfma_f32_16x16x32_bf16 v[14:17], v[74:77], v[38:41], v[14:17]
	s_barrier
	ds_write2st64_b32 v8, v30, v31 offset1:1
	ds_write2st64_b32 v8, v32, v33 offset0:2 offset1:3
	v_mfma_f32_16x16x32_bf16 v[30:33], v[70:73], v[50:53], v[42:45]
	ds_write2st64_b32 v8, v26, v27 offset0:4 offset1:5
	ds_write2st64_b32 v8, v28, v29 offset0:6 offset1:7
	s_nop 5
	ds_write2st64_b32 v8, v30, v31 offset0:8 offset1:9
	v_mfma_f32_16x16x32_bf16 v[22:25], v[74:77], v[58:61], v[22:25]
	s_waitcnt vmcnt(0)
	v_mfma_f32_16x16x32_bf16 v[14:17], v[46:49], v[50:53], v[14:17]
	ds_write2st64_b32 v8, v32, v33 offset0:10 offset1:11
	s_nop 6
	ds_write2st64_b32 v8, v14, v15 offset0:12 offset1:13
	ds_write2st64_b32 v8, v16, v17 offset0:14 offset1:15
	v_mfma_f32_16x16x32_bf16 v[14:17], v[66:69], v[62:65], v[18:21]
	ds_write2st64_b32 v8, v10, v11 offset0:16 offset1:17
	ds_write2st64_b32 v8, v12, v13 offset0:18 offset1:19
	s_nop 5
	ds_write2st64_b32 v8, v14, v15 offset0:20 offset1:21
	v_mfma_f32_16x16x32_bf16 v[10:13], v[70:73], v[62:65], v[34:37]
	ds_write2st64_b32 v8, v16, v17 offset0:22 offset1:23
	s_nop 6
	ds_write2st64_b32 v8, v10, v11 offset0:24 offset1:25
	ds_write2st64_b32 v8, v12, v13 offset0:26 offset1:27
	v_mfma_f32_16x16x32_bf16 v[10:13], v[46:49], v[62:65], v[22:25]
	s_nop 7
	ds_write2st64_b32 v8, v10, v11 offset0:28 offset1:29
	ds_write2st64_b32 v8, v12, v13 offset0:30 offset1:31
	s_waitcnt lgkmcnt(0)
	s_barrier
	s_and_saveexec_b64 s[12:13], vcc
	s_cbranch_execz .LBB0_770
	ds_read2st64_b32 v[10:11], v6 offset1:1
	ds_read2st64_b32 v[12:13], v6 offset0:8 offset1:9
	ds_read2st64_b32 v[14:15], v6 offset0:10 offset1:11
	ds_read2st64_b32 v[16:17], v6 offset0:2 offset1:3
	s_waitcnt lgkmcnt(3)
	v_add_f32_e32 v0, 0, v10
	s_waitcnt lgkmcnt(2)
	v_add_f32_e32 v18, 0, v12
	v_add_f32_e32 v19, 0, v11
	v_add_f32_e32 v20, 0, v13
	ds_read2st64_b32 v[10:11], v6 offset0:32 offset1:33
	ds_read2st64_b32 v[12:13], v6 offset0:40 offset1:41
	s_waitcnt lgkmcnt(2)
	v_add_f32_e32 v21, 0, v16
	v_add_f32_e32 v22, 0, v14
	v_add_f32_e32 v23, 0, v17
	v_add_f32_e32 v24, 0, v15
	ds_read2st64_b32 v[14:15], v6 offset0:42 offset1:43
	ds_read2st64_b32 v[16:17], v6 offset0:34 offset1:35
	s_waitcnt lgkmcnt(3)
	v_add_f32_e32 v0, v0, v10
	s_waitcnt lgkmcnt(2)
	v_add_f32_e32 v18, v18, v12
	v_add_f32_e32 v19, v19, v11
	v_add_f32_e32 v20, v20, v13
	ds_read2st64_b32 v[10:11], v6 offset0:64 offset1:65
	ds_read2st64_b32 v[12:13], v6 offset0:72 offset1:73
	s_waitcnt lgkmcnt(2)
	v_add_f32_e32 v21, v21, v16
	v_add_f32_e32 v22, v22, v14
	v_add_f32_e32 v23, v23, v17
	v_add_f32_e32 v24, v24, v15
	ds_read2st64_b32 v[14:15], v6 offset0:74 offset1:75
	ds_read2st64_b32 v[16:17], v6 offset0:66 offset1:67
	s_waitcnt lgkmcnt(3)
	v_add_f32_e32 v0, v0, v10
	s_waitcnt lgkmcnt(2)
	v_add_f32_e32 v18, v18, v12
	v_add_f32_e32 v19, v19, v11
	v_add_f32_e32 v20, v20, v13
	ds_read2st64_b32 v[10:11], v6 offset0:96 offset1:97
	ds_read2st64_b32 v[12:13], v6 offset0:104 offset1:105
	s_waitcnt lgkmcnt(2)
	v_add_f32_e32 v21, v21, v16
	v_add_f32_e32 v22, v22, v14
	v_add_f32_e32 v23, v23, v17
	v_add_f32_e32 v24, v24, v15
	ds_read2st64_b32 v[14:15], v6 offset0:106 offset1:107
	ds_read2st64_b32 v[16:17], v6 offset0:98 offset1:99
	s_waitcnt lgkmcnt(3)
	v_add_f32_e32 v0, v0, v10
	s_waitcnt lgkmcnt(2)
	v_add_f32_e32 v18, v18, v12
	v_add_f32_e32 v19, v19, v11
	v_add_f32_e32 v20, v20, v13
	ds_read2st64_b32 v[10:11], v6 offset0:128 offset1:129
	ds_read2st64_b32 v[12:13], v6 offset0:136 offset1:137
	s_waitcnt lgkmcnt(2)
	v_add_f32_e32 v21, v21, v16
	v_add_f32_e32 v22, v22, v14
	v_add_f32_e32 v23, v23, v17
	v_add_f32_e32 v24, v24, v15
	ds_read2st64_b32 v[14:15], v6 offset0:138 offset1:139
	ds_read2st64_b32 v[16:17], v6 offset0:130 offset1:131
	s_waitcnt lgkmcnt(3)
	v_add_f32_e32 v0, v0, v10
	s_waitcnt lgkmcnt(2)
	v_add_f32_e32 v18, v18, v12
	v_add_f32_e32 v19, v19, v11
	v_add_f32_e32 v20, v20, v13
	ds_read2st64_b32 v[10:11], v6 offset0:160 offset1:161
	ds_read2st64_b32 v[12:13], v6 offset0:168 offset1:169
	s_waitcnt lgkmcnt(2)
	v_add_f32_e32 v21, v21, v16
	v_add_f32_e32 v22, v22, v14
	v_add_f32_e32 v23, v23, v17
	v_add_f32_e32 v24, v24, v15
	ds_read2st64_b32 v[14:15], v6 offset0:170 offset1:171
	ds_read2st64_b32 v[16:17], v6 offset0:162 offset1:163
	s_waitcnt lgkmcnt(3)
	v_add_f32_e32 v0, v0, v10
	s_waitcnt lgkmcnt(2)
	v_add_f32_e32 v18, v18, v12
	v_add_f32_e32 v19, v19, v11
	v_add_f32_e32 v20, v20, v13
	ds_read2st64_b32 v[10:11], v6 offset0:192 offset1:193
	ds_read2st64_b32 v[12:13], v6 offset0:200 offset1:201
	s_waitcnt lgkmcnt(2)
	v_add_f32_e32 v21, v21, v16
	v_add_f32_e32 v22, v22, v14
	v_add_f32_e32 v23, v23, v17
	v_add_f32_e32 v24, v24, v15
	ds_read2st64_b32 v[14:15], v6 offset0:202 offset1:203
	ds_read2st64_b32 v[16:17], v6 offset0:194 offset1:195
	s_waitcnt lgkmcnt(3)
	v_add_f32_e32 v0, v0, v10
	s_waitcnt lgkmcnt(2)
	v_add_f32_e32 v18, v18, v12
	v_add_f32_e32 v19, v19, v11
	v_add_f32_e32 v20, v20, v13
	ds_read2st64_b32 v[10:11], v6 offset0:224 offset1:225
	ds_read2st64_b32 v[12:13], v6 offset0:232 offset1:233
	s_waitcnt lgkmcnt(2)
	v_add_f32_e32 v21, v21, v16
	v_add_f32_e32 v22, v22, v14
	v_add_f32_e32 v23, v23, v17
	v_add_f32_e32 v24, v24, v15
	ds_read2st64_b32 v[14:15], v6 offset0:234 offset1:235
	ds_read2st64_b32 v[16:17], v6 offset0:226 offset1:227
	s_waitcnt lgkmcnt(3)
	v_add_f32_e32 v11, v19, v11
	s_waitcnt lgkmcnt(2)
	v_add_f32_e32 v19, v20, v13
	v_add_f32_e32 v25, v0, v10
	v_add_f32_e32 v18, v18, v12
	v_mul_f32_e32 v0, v11, v11
	v_mul_f32_e32 v10, v19, v19
	s_waitcnt lgkmcnt(0)
	v_add_f32_e32 v16, v21, v16
	v_add_f32_e32 v20, v22, v14
	v_fmac_f32_e32 v0, v25, v25
	v_fmac_f32_e32 v10, v18, v18
	v_add_f32_e32 v17, v23, v17
	v_add_f32_e32 v21, v24, v15
	v_fmac_f32_e32 v0, v16, v16
	v_fmac_f32_e32 v10, v20, v20
	v_fmac_f32_e32 v0, v17, v17
	v_fmac_f32_e32 v10, v21, v21
	v_add_f32_e32 v13, v0, v10
	v_and_b32_e32 v10, 64, v9
	v_xor_b32_e32 v0, 1, v9
	v_add_u32_e32 v22, 64, v10
	v_cmp_lt_i32_e64 s[4:5], v0, v22
	v_or_b32_e32 v10, s9, v182
	v_or_b32_e32 v12, s8, v7
	v_cndmask_b32_e64 v0, v9, v0, s[4:5]
	v_lshlrev_b32_e32 v0, 2, v0
	ds_bpermute_b32 v23, v0, v13
	v_lshlrev_b32_e32 v0, 11, v10
	v_lshl_add_u64 v[14:15], s[58:59], 0, v[0:1]
	s_waitcnt lgkmcnt(0)
	v_add_f32_e32 v0, v13, v23
	v_xor_b32_e32 v13, 2, v9
	v_cmp_lt_i32_e64 s[4:5], v13, v22
	s_nop 1
	v_cndmask_b32_e64 v13, v9, v13, s[4:5]
	v_lshlrev_b32_e32 v13, 2, v13
	ds_bpermute_b32 v23, v13, v0
	v_ashrrev_i32_e32 v13, 31, v12
	v_lshl_add_u64 v[12:13], v[12:13], 1, v[14:15]
	v_cvt_pk_bf16_f32 v14, v25, v11
	v_xor_b32_e32 v11, 4, v9
	v_cmp_lt_i32_e64 s[4:5], v11, v22
	s_waitcnt lgkmcnt(0)
	v_add_f32_e32 v0, v0, v23
	v_cvt_pk_bf16_f32 v15, v16, v17
	global_store_dwordx2 v[12:13], v[14:15], off sc1
	v_cndmask_b32_e64 v11, v9, v11, s[4:5]
	v_lshlrev_b32_e32 v11, 2, v11
	ds_bpermute_b32 v11, v11, v0
	v_cvt_pk_bf16_f32 v14, v18, v19
	v_cvt_pk_bf16_f32 v15, v20, v21
	global_store_dwordx2 v[12:13], v[14:15], off offset:256 sc1
	s_and_b64 exec, exec, s[0:1]
	s_cbranch_execz .LBB0_770
	s_lshl_b32 s4, s19, 2
	s_or_b32 s4, s4, s20
	s_mul_hi_i32 s5, s4, 0x10800
	s_mul_i32 s4, s4, 0x10800
	s_add_u32 s4, s44, s4
	s_waitcnt lgkmcnt(0)
	v_add_f32_e32 v0, v0, v11
	s_addc_u32 s5, s45, s5
	v_lshlrev_b32_e32 v10, 2, v10
	global_store_dword v10, v0, s[4:5] sc1
	s_branch .LBB0_770

.LBB0_784:
	s_nop 7
	v_xor_b32_e32 v138, 16, v137
	v_xor_b32_e32 v139, 32, v137
	v_lshlrev_b32_e32 v138, 2, v138
	v_lshlrev_b32_e32 v139, 2, v139
	v_mul_f32_e32 v140, v124, v124
	v_mul_f32_e32 v141, v108, v108
	v_mul_f32_e32 v142, v92, v92
	v_mul_f32_e32 v143, v76, v76
	v_mul_f32_e32 v144, v60, v60
	v_mul_f32_e32 v145, v44, v44
	v_mul_f32_e32 v146, v28, v28
	v_mul_f32_e32 v147, v12, v12
	v_fmac_f32_e32 v140, v125, v125
	v_fmac_f32_e32 v141, v109, v109
	v_fmac_f32_e32 v142, v93, v93
	v_fmac_f32_e32 v143, v77, v77
	v_fmac_f32_e32 v144, v61, v61
	v_fmac_f32_e32 v145, v45, v45
	v_fmac_f32_e32 v146, v29, v29
	v_fmac_f32_e32 v147, v13, v13
	v_fmac_f32_e32 v140, v126, v126
	v_fmac_f32_e32 v141, v110, v110
	v_fmac_f32_e32 v142, v94, v94
	v_fmac_f32_e32 v143, v78, v78
	v_fmac_f32_e32 v144, v62, v62
	v_fmac_f32_e32 v145, v46, v46
	v_fmac_f32_e32 v146, v30, v30
	v_fmac_f32_e32 v147, v14, v14
	v_fmac_f32_e32 v140, v127, v127
	v_fmac_f32_e32 v141, v111, v111
	v_fmac_f32_e32 v142, v95, v95
	v_fmac_f32_e32 v143, v79, v79
	v_fmac_f32_e32 v144, v63, v63
	v_fmac_f32_e32 v145, v47, v47
	v_fmac_f32_e32 v146, v31, v31
	v_fmac_f32_e32 v147, v15, v15
	v_fmac_f32_e32 v140, v112, v112
	v_fmac_f32_e32 v141, v96, v96
	v_fmac_f32_e32 v142, v80, v80
	v_fmac_f32_e32 v143, v64, v64
	v_fmac_f32_e32 v144, v48, v48
	v_fmac_f32_e32 v145, v32, v32
	v_fmac_f32_e32 v146, v16, v16
	v_fmac_f32_e32 v147, v0, v0
	v_fmac_f32_e32 v140, v113, v113
	v_fmac_f32_e32 v141, v97, v97
	v_fmac_f32_e32 v142, v81, v81
	v_fmac_f32_e32 v143, v65, v65
	v_fmac_f32_e32 v144, v49, v49
	v_fmac_f32_e32 v145, v33, v33
	v_fmac_f32_e32 v146, v17, v17
	v_fmac_f32_e32 v147, v1, v1
	v_fmac_f32_e32 v140, v114, v114
	v_fmac_f32_e32 v141, v98, v98
	v_fmac_f32_e32 v142, v82, v82
	v_fmac_f32_e32 v143, v66, v66
	v_fmac_f32_e32 v144, v50, v50
	v_fmac_f32_e32 v145, v34, v34
	v_fmac_f32_e32 v146, v18, v18
	v_fmac_f32_e32 v147, v2, v2
	v_fmac_f32_e32 v140, v115, v115
	v_fmac_f32_e32 v141, v99, v99
	v_fmac_f32_e32 v142, v83, v83
	v_fmac_f32_e32 v143, v67, v67
	v_fmac_f32_e32 v144, v51, v51
	v_fmac_f32_e32 v145, v35, v35
	v_fmac_f32_e32 v146, v19, v19
	v_fmac_f32_e32 v147, v3, v3
	v_fmac_f32_e32 v140, v120, v120
	v_fmac_f32_e32 v141, v100, v100
	v_fmac_f32_e32 v142, v84, v84
	v_fmac_f32_e32 v143, v68, v68
	v_fmac_f32_e32 v144, v52, v52
	v_fmac_f32_e32 v145, v36, v36
	v_fmac_f32_e32 v146, v20, v20
	v_fmac_f32_e32 v147, v4, v4
	v_fmac_f32_e32 v140, v121, v121
	v_fmac_f32_e32 v141, v101, v101
	v_fmac_f32_e32 v142, v85, v85
	v_fmac_f32_e32 v143, v69, v69
	v_fmac_f32_e32 v144, v53, v53
	v_fmac_f32_e32 v145, v37, v37
	v_fmac_f32_e32 v146, v21, v21
	v_fmac_f32_e32 v147, v5, v5
	v_fmac_f32_e32 v140, v122, v122
	v_fmac_f32_e32 v141, v102, v102
	v_fmac_f32_e32 v142, v86, v86
	v_fmac_f32_e32 v143, v70, v70
	v_fmac_f32_e32 v144, v54, v54
	v_fmac_f32_e32 v145, v38, v38
	v_fmac_f32_e32 v146, v22, v22
	v_fmac_f32_e32 v147, v6, v6
	v_fmac_f32_e32 v140, v123, v123
	v_fmac_f32_e32 v141, v103, v103
	v_fmac_f32_e32 v142, v87, v87
	v_fmac_f32_e32 v143, v71, v71
	v_fmac_f32_e32 v144, v55, v55
	v_fmac_f32_e32 v145, v39, v39
	v_fmac_f32_e32 v146, v23, v23
	v_fmac_f32_e32 v147, v7, v7
	v_fmac_f32_e32 v140, v116, v116
	v_fmac_f32_e32 v141, v104, v104
	v_fmac_f32_e32 v142, v88, v88
	v_fmac_f32_e32 v143, v72, v72
	v_fmac_f32_e32 v144, v56, v56
	v_fmac_f32_e32 v145, v40, v40
	v_fmac_f32_e32 v146, v24, v24
	v_fmac_f32_e32 v147, v8, v8
	v_fmac_f32_e32 v140, v117, v117
	v_fmac_f32_e32 v141, v105, v105
	v_fmac_f32_e32 v142, v89, v89
	v_fmac_f32_e32 v143, v73, v73
	v_fmac_f32_e32 v144, v57, v57
	v_fmac_f32_e32 v145, v41, v41
	v_fmac_f32_e32 v146, v25, v25
	v_fmac_f32_e32 v147, v9, v9
	v_fmac_f32_e32 v140, v118, v118
	v_fmac_f32_e32 v141, v106, v106
	v_fmac_f32_e32 v142, v90, v90
	v_fmac_f32_e32 v143, v74, v74
	v_fmac_f32_e32 v144, v58, v58
	v_fmac_f32_e32 v145, v42, v42
	v_fmac_f32_e32 v146, v26, v26
	v_fmac_f32_e32 v147, v10, v10
	v_fmac_f32_e32 v140, v119, v119
	v_fmac_f32_e32 v141, v107, v107
	v_fmac_f32_e32 v142, v91, v91
	v_fmac_f32_e32 v143, v75, v75
	v_fmac_f32_e32 v144, v59, v59
	v_fmac_f32_e32 v145, v43, v43
	v_fmac_f32_e32 v146, v27, v27
	v_fmac_f32_e32 v147, v11, v11
	ds_bpermute_b32 v148, v138, v140
	ds_bpermute_b32 v149, v138, v141
	ds_bpermute_b32 v150, v138, v142
	ds_bpermute_b32 v151, v138, v143
	ds_bpermute_b32 v152, v138, v144
	ds_bpermute_b32 v153, v138, v145
	ds_bpermute_b32 v154, v138, v146
	ds_bpermute_b32 v155, v138, v147
	s_waitcnt lgkmcnt(0)
	v_add_f32_e32 v140, v140, v148
	v_add_f32_e32 v141, v141, v149
	v_add_f32_e32 v142, v142, v150
	v_add_f32_e32 v143, v143, v151
	v_add_f32_e32 v144, v144, v152
	v_add_f32_e32 v145, v145, v153
	v_add_f32_e32 v146, v146, v154
	v_add_f32_e32 v147, v147, v155
	ds_bpermute_b32 v148, v139, v140
	ds_bpermute_b32 v149, v139, v141
	ds_bpermute_b32 v150, v139, v142
	ds_bpermute_b32 v151, v139, v143
	ds_bpermute_b32 v152, v139, v144
	ds_bpermute_b32 v153, v139, v145
	ds_bpermute_b32 v154, v139, v146
	ds_bpermute_b32 v155, v139, v147
	s_waitcnt lgkmcnt(0)
	v_add_f32_e32 v140, v140, v148
	v_add_f32_e32 v141, v141, v149
	v_add_f32_e32 v142, v142, v150
	v_add_f32_e32 v143, v143, v151
	v_add_f32_e32 v144, v144, v152
	v_add_f32_e32 v145, v145, v153
	v_add_f32_e32 v146, v146, v154
	v_add_f32_e32 v147, v147, v155
	s_and_b32 s98, s2, 7
	s_lshl_b32 s98, s98, 3
	s_bfe_u32 s99, s2, 0x30003
	s_or_b32 s98, s98, s99
	s_lshr_b32 s99, s2, 6
	s_mul_i32 s99, s99, 0x42000
	s_lshl_b32 s98, s98, 10
	s_add_u32 s100, s44, s99
	s_addc_u32 s101, s45, 0
	s_add_u32 s100, s100, s98
	s_addc_u32 s101, s101, 0
	v_lshrrev_b32_e32 v158, 8, v136
	v_bfe_u32 v159, v136, 6, 2
	v_and_b32_e32 v160, 15, v136
	v_lshl_add_u32 v160, v158, 6, v160
	v_mul_u32_u24_e32 v159, 0x4200, v159
	v_add_u32_e32 v160, v160, v159
	v_lshlrev_b32_e32 v160, 2, v160
	v_bfe_u32 v161, v136, 4, 2
	v_cmp_eq_u32_e32 vcc, 0, v161
	s_and_saveexec_b64 s[0:1], vcc
	global_store_dword v160, v140, s[100:101] sc1
	global_store_dword v160, v141, s[100:101] offset:64 sc1
	global_store_dword v160, v142, s[100:101] offset:128 sc1
	global_store_dword v160, v143, s[100:101] offset:192 sc1
	global_store_dword v160, v144, s[100:101] offset:512 sc1
	global_store_dword v160, v145, s[100:101] offset:576 sc1
	global_store_dword v160, v146, s[100:101] offset:640 sc1
	global_store_dword v160, v147, s[100:101] offset:704 sc1
	s_or_b64 exec, exec, s[0:1]
	s_branch .LBB0_776

.LBB0_832:
	s_andn2_saveexec_b64 s[6:7], s[6:7]
	s_cbranch_execz .LBB0_852
	s_mov_b64 s[6:7], exec
	s_waitcnt lgkmcnt(0)
	s_waitcnt vmcnt(0)
	buffer_inv sc1
	v_mbcnt_lo_u32_b32 v141, s6, 0
	v_mbcnt_hi_u32_b32 v141, s7, v141
	v_cmp_eq_u32_e32 vcc, 0, v141
	s_and_saveexec_b64 s[8:9], vcc
	s_cbranch_execz .LBB0_835
	s_bcnt1_i32_b64 s3, s[6:7]
	v_mov_b32_e32 v142, 0x3000
	v_mov_b32_e32 v143, s3
	global_atomic_add v142, v142, v143, s[54:55] offset:1024 sc0

.LBB0_1162:
	s_ashr_i32 s21, s20, 6
	s_bfe_u32 s22, s20, 0x20004
	s_lshl_b32 s6, s21, 8
	s_lshl_b32 s7, s22, 5
	s_or_b32 s12, s7, s6
	s_and_b32 s10, s3, 0x1e0
	s_ashr_i32 s13, s12, 31
	s_lshl_b64 s[6:7], s[12:13], 11
	s_or_b32 s13, s10, 0x4000
	s_lshl_b32 s10, s13, 11
	v_lshl_add_u64 v[72:73], v[2:3], 0, s[10:11]
	v_lshl_add_u64 v[70:71], v[4:5], 0, s[6:7]
	v_add_co_u32_e64 v74, s[6:7], s17, v72
	s_waitcnt lgkmcnt(0)
	global_load_dwordx4 v[10:13], v[70:71], off
	v_addc_co_u32_e64 v75, s[6:7], 0, v73, s[6:7]
	v_add_co_u32_e64 v76, s[6:7], s17, v70
	global_load_dwordx4 v[14:17], v[72:73], off
	s_nop 0
	v_addc_co_u32_e64 v77, s[6:7], 0, v71, s[6:7]
	v_add_co_u32_e64 v78, s[6:7], s18, v70
	global_load_dwordx4 v[18:21], v[72:73], off offset:64
	global_load_dwordx4 v[22:25], v[74:75], off
	v_addc_co_u32_e64 v79, s[6:7], 0, v71, s[6:7]
	v_add_co_u32_e64 v80, s[6:7], s19, v70
	global_load_dwordx4 v[26:29], v[70:71], off offset:64
	s_nop 0
	v_addc_co_u32_e64 v81, s[6:7], 0, v71, s[6:7]
	global_load_dwordx4 v[34:37], v[76:77], off
	global_load_dwordx4 v[38:41], v[74:75], off offset:64
	global_load_dwordx4 v[42:45], v[76:77], off offset:64
	global_load_dwordx4 v[50:53], v[78:79], off
	global_load_dwordx4 v[54:57], v[78:79], off offset:64
	global_load_dwordx4 v[62:65], v[80:81], off
	global_load_dwordx4 v[66:69], v[80:81], off offset:64
	s_waitcnt vmcnt(10)
	v_mfma_f32_16x16x32_bf16 v[30:33], v[10:13], v[14:17], 0
	s_waitcnt vmcnt(8)
	v_mfma_f32_16x16x32_bf16 v[10:13], v[10:13], v[22:25], 0
	s_waitcnt vmcnt(6)
	v_mfma_f32_16x16x32_bf16 v[46:49], v[34:37], v[14:17], 0
	v_mfma_f32_16x16x32_bf16 v[34:37], v[34:37], v[22:25], 0
	s_waitcnt vmcnt(3)
	v_mfma_f32_16x16x32_bf16 v[58:61], v[50:53], v[14:17], 0
	s_waitcnt vmcnt(1)
	v_mfma_f32_16x16x32_bf16 v[14:17], v[62:65], v[14:17], 0
	v_mfma_f32_16x16x32_bf16 v[30:33], v[26:29], v[18:21], v[30:33]
	v_mfma_f32_16x16x32_bf16 v[10:13], v[26:29], v[38:41], v[10:13]
	v_mfma_f32_16x16x32_bf16 v[26:29], v[42:45], v[18:21], v[46:49]
	v_mfma_f32_16x16x32_bf16 v[34:37], v[42:45], v[38:41], v[34:37]
	v_mfma_f32_16x16x32_bf16 v[42:45], v[54:57], v[18:21], v[58:61]
	s_waitcnt vmcnt(0)
	v_mfma_f32_16x16x32_bf16 v[14:17], v[66:69], v[18:21], v[14:17]
	global_load_dwordx4 v[18:21], v[70:71], off offset:128
	v_mfma_f32_16x16x32_bf16 v[50:53], v[50:53], v[22:25], 0
	v_mfma_f32_16x16x32_bf16 v[22:25], v[62:65], v[22:25], 0
	v_mfma_f32_16x16x32_bf16 v[46:49], v[54:57], v[38:41], v[50:53]
	v_mfma_f32_16x16x32_bf16 v[22:25], v[66:69], v[38:41], v[22:25]
	global_load_dwordx4 v[38:41], v[72:73], off offset:128
	s_nop 3
	global_load_dwordx4 v[50:53], v[72:73], off offset:192
	global_load_dwordx4 v[54:57], v[70:71], off offset:192
	global_load_dwordx4 v[58:61], v[74:75], off offset:128
	global_load_dwordx4 v[62:65], v[74:75], off offset:192
	s_waitcnt vmcnt(4)
	v_mfma_f32_16x16x32_bf16 v[30:33], v[18:21], v[38:41], v[30:33]
	s_waitcnt vmcnt(1)
	v_mfma_f32_16x16x32_bf16 v[10:13], v[18:21], v[58:61], v[10:13]
	global_load_dwordx4 v[18:21], v[76:77], off offset:128
	global_load_dwordx4 v[66:69], v[76:77], off offset:192
	v_mfma_f32_16x16x32_bf16 v[30:33], v[54:57], v[50:53], v[30:33]
	s_waitcnt vmcnt(2)
	v_mfma_f32_16x16x32_bf16 v[10:13], v[54:57], v[62:65], v[10:13]
	s_waitcnt vmcnt(1)
	v_mfma_f32_16x16x32_bf16 v[26:29], v[18:21], v[38:41], v[26:29]
	v_mfma_f32_16x16x32_bf16 v[18:21], v[18:21], v[58:61], v[34:37]
	s_nop 2
	global_load_dwordx4 v[34:37], v[78:79], off offset:128
	global_load_dwordx4 v[70:73], v[78:79], off offset:192
	global_load_dwordx4 v[74:77], v[80:81], off offset:128
	s_waitcnt vmcnt(3)
	v_mfma_f32_16x16x32_bf16 v[26:29], v[66:69], v[50:53], v[26:29]
	s_waitcnt vmcnt(2)
	v_mfma_f32_16x16x32_bf16 v[42:45], v[34:37], v[38:41], v[42:45]
	v_mfma_f32_16x16x32_bf16 v[34:37], v[34:37], v[58:61], v[46:49]
	s_nop 2
	global_load_dwordx4 v[46:49], v[80:81], off offset:192
	s_waitcnt vmcnt(1)
	v_mfma_f32_16x16x32_bf16 v[14:17], v[74:77], v[38:41], v[14:17]
	s_barrier
	ds_write2st64_b32 v8, v30, v31 offset1:1
	ds_write2st64_b32 v8, v32, v33 offset0:2 offset1:3
	v_mfma_f32_16x16x32_bf16 v[30:33], v[70:73], v[50:53], v[42:45]
	ds_write2st64_b32 v8, v26, v27 offset0:4 offset1:5
	ds_write2st64_b32 v8, v28, v29 offset0:6 offset1:7
	s_nop 5
	ds_write2st64_b32 v8, v30, v31 offset0:8 offset1:9
	v_mfma_f32_16x16x32_bf16 v[22:25], v[74:77], v[58:61], v[22:25]
	s_waitcnt vmcnt(0)
	v_mfma_f32_16x16x32_bf16 v[14:17], v[46:49], v[50:53], v[14:17]
	ds_write2st64_b32 v8, v32, v33 offset0:10 offset1:11
	s_nop 6
	ds_write2st64_b32 v8, v14, v15 offset0:12 offset1:13
	ds_write2st64_b32 v8, v16, v17 offset0:14 offset1:15
	v_mfma_f32_16x16x32_bf16 v[14:17], v[66:69], v[62:65], v[18:21]
	ds_write2st64_b32 v8, v10, v11 offset0:16 offset1:17
	ds_write2st64_b32 v8, v12, v13 offset0:18 offset1:19
	s_nop 5
	ds_write2st64_b32 v8, v14, v15 offset0:20 offset1:21
	v_mfma_f32_16x16x32_bf16 v[10:13], v[70:73], v[62:65], v[34:37]
	ds_write2st64_b32 v8, v16, v17 offset0:22 offset1:23
	s_nop 6
	ds_write2st64_b32 v8, v10, v11 offset0:24 offset1:25
	ds_write2st64_b32 v8, v12, v13 offset0:26 offset1:27
	v_mfma_f32_16x16x32_bf16 v[10:13], v[46:49], v[62:65], v[22:25]
	s_nop 7
	ds_write2st64_b32 v8, v10, v11 offset0:28 offset1:29
	ds_write2st64_b32 v8, v12, v13 offset0:30 offset1:31
	s_waitcnt lgkmcnt(0)
	s_barrier
	s_and_saveexec_b64 s[14:15], vcc
	s_cbranch_execz .LBB0_1161
	ds_read2st64_b32 v[10:11], v6 offset1:1
	ds_read2st64_b32 v[12:13], v6 offset0:8 offset1:9
	ds_read2st64_b32 v[14:15], v6 offset0:10 offset1:11
	ds_read2st64_b32 v[16:17], v6 offset0:2 offset1:3
	s_waitcnt lgkmcnt(3)
	v_add_f32_e32 v0, 0, v10
	s_waitcnt lgkmcnt(2)
	v_add_f32_e32 v9, 0, v12
	v_add_f32_e32 v18, 0, v11
	v_add_f32_e32 v19, 0, v13
	ds_read2st64_b32 v[10:11], v6 offset0:32 offset1:33
	ds_read2st64_b32 v[12:13], v6 offset0:40 offset1:41
	s_waitcnt lgkmcnt(2)
	v_add_f32_e32 v20, 0, v16
	v_add_f32_e32 v21, 0, v14
	v_add_f32_e32 v22, 0, v17
	v_add_f32_e32 v23, 0, v15
	ds_read2st64_b32 v[14:15], v6 offset0:42 offset1:43
	ds_read2st64_b32 v[16:17], v6 offset0:34 offset1:35
	s_waitcnt lgkmcnt(3)
	v_add_f32_e32 v0, v0, v10
	s_waitcnt lgkmcnt(2)
	v_add_f32_e32 v9, v9, v12
	v_add_f32_e32 v18, v18, v11
	v_add_f32_e32 v19, v19, v13
	ds_read2st64_b32 v[10:11], v6 offset0:64 offset1:65
	ds_read2st64_b32 v[12:13], v6 offset0:72 offset1:73
	s_waitcnt lgkmcnt(2)
	v_add_f32_e32 v20, v20, v16
	v_add_f32_e32 v21, v21, v14
	v_add_f32_e32 v22, v22, v17
	v_add_f32_e32 v23, v23, v15
	ds_read2st64_b32 v[14:15], v6 offset0:74 offset1:75
	ds_read2st64_b32 v[16:17], v6 offset0:66 offset1:67
	s_waitcnt lgkmcnt(3)
	v_add_f32_e32 v0, v0, v10
	s_waitcnt lgkmcnt(2)
	v_add_f32_e32 v9, v9, v12
	v_add_f32_e32 v18, v18, v11
	v_add_f32_e32 v19, v19, v13
	ds_read2st64_b32 v[10:11], v6 offset0:96 offset1:97
	ds_read2st64_b32 v[12:13], v6 offset0:104 offset1:105
	s_waitcnt lgkmcnt(2)
	v_add_f32_e32 v20, v20, v16
	v_add_f32_e32 v21, v21, v14
	v_add_f32_e32 v22, v22, v17
	v_add_f32_e32 v23, v23, v15
	ds_read2st64_b32 v[14:15], v6 offset0:106 offset1:107
	ds_read2st64_b32 v[16:17], v6 offset0:98 offset1:99
	s_waitcnt lgkmcnt(3)
	v_add_f32_e32 v0, v0, v10
	s_waitcnt lgkmcnt(2)
	v_add_f32_e32 v9, v9, v12
	v_add_f32_e32 v18, v18, v11
	v_add_f32_e32 v19, v19, v13
	ds_read2st64_b32 v[10:11], v6 offset0:128 offset1:129
	ds_read2st64_b32 v[12:13], v6 offset0:136 offset1:137
	s_waitcnt lgkmcnt(2)
	v_add_f32_e32 v20, v20, v16
	v_add_f32_e32 v21, v21, v14
	v_add_f32_e32 v22, v22, v17
	v_add_f32_e32 v23, v23, v15
	ds_read2st64_b32 v[14:15], v6 offset0:138 offset1:139
	ds_read2st64_b32 v[16:17], v6 offset0:130 offset1:131
	s_waitcnt lgkmcnt(3)
	v_add_f32_e32 v0, v0, v10
	s_waitcnt lgkmcnt(2)
	v_add_f32_e32 v9, v9, v12
	v_add_f32_e32 v18, v18, v11
	v_add_f32_e32 v19, v19, v13
	ds_read2st64_b32 v[10:11], v6 offset0:160 offset1:161
	ds_read2st64_b32 v[12:13], v6 offset0:168 offset1:169
	s_waitcnt lgkmcnt(2)
	v_add_f32_e32 v20, v20, v16
	v_add_f32_e32 v21, v21, v14
	v_add_f32_e32 v22, v22, v17
	v_add_f32_e32 v23, v23, v15
	ds_read2st64_b32 v[14:15], v6 offset0:170 offset1:171
	ds_read2st64_b32 v[16:17], v6 offset0:162 offset1:163
	s_waitcnt lgkmcnt(3)
	v_add_f32_e32 v0, v0, v10
	s_waitcnt lgkmcnt(2)
	v_add_f32_e32 v9, v9, v12
	v_add_f32_e32 v18, v18, v11
	v_add_f32_e32 v19, v19, v13
	ds_read2st64_b32 v[10:11], v6 offset0:192 offset1:193
	ds_read2st64_b32 v[12:13], v6 offset0:200 offset1:201
	s_waitcnt lgkmcnt(2)
	v_add_f32_e32 v20, v20, v16
	v_add_f32_e32 v21, v21, v14
	v_add_f32_e32 v22, v22, v17
	v_add_f32_e32 v23, v23, v15
	ds_read2st64_b32 v[14:15], v6 offset0:202 offset1:203
	ds_read2st64_b32 v[16:17], v6 offset0:194 offset1:195
	s_waitcnt lgkmcnt(3)
	v_add_f32_e32 v0, v0, v10
	s_waitcnt lgkmcnt(2)
	v_add_f32_e32 v9, v9, v12
	v_add_f32_e32 v18, v18, v11
	v_add_f32_e32 v19, v19, v13
	ds_read2st64_b32 v[10:11], v6 offset0:224 offset1:225
	ds_read2st64_b32 v[12:13], v6 offset0:232 offset1:233
	s_waitcnt lgkmcnt(2)
	v_add_f32_e32 v20, v20, v16
	v_add_f32_e32 v21, v21, v14
	v_add_f32_e32 v22, v22, v17
	v_add_f32_e32 v23, v23, v15
	ds_read2st64_b32 v[14:15], v6 offset0:234 offset1:235
	ds_read2st64_b32 v[16:17], v6 offset0:226 offset1:227
	s_waitcnt lgkmcnt(3)
	v_add_f32_e32 v18, v18, v11
	s_waitcnt lgkmcnt(2)
	v_add_f32_e32 v19, v19, v13
	v_add_f32_e32 v24, v0, v10
	v_add_f32_e32 v25, v9, v12
	v_mul_f32_e32 v0, v18, v18
	v_mul_f32_e32 v9, v19, v19
	s_waitcnt lgkmcnt(0)
	v_add_f32_e32 v16, v20, v16
	v_add_f32_e32 v20, v21, v14
	v_fmac_f32_e32 v0, v24, v24
	v_fmac_f32_e32 v9, v25, v25
	v_add_f32_e32 v17, v22, v17
	v_add_f32_e32 v21, v23, v15
	v_fmac_f32_e32 v0, v16, v16
	v_fmac_f32_e32 v9, v20, v20
	v_fmac_f32_e32 v0, v17, v17
	v_fmac_f32_e32 v9, v21, v21
	v_add_f32_e32 v11, v0, v9
	v_and_b32_e32 v9, 64, v137
	v_xor_b32_e32 v0, 1, v137
	v_add_u32_e32 v22, 64, v9
	v_cmp_lt_i32_e64 s[6:7], v0, v22
	v_or_b32_e32 v9, s13, v182
	v_or_b32_e32 v10, s12, v7
	v_cndmask_b32_e64 v0, v137, v0, s[6:7]
	v_lshlrev_b32_e32 v0, 2, v0
	ds_bpermute_b32 v14, v0, v11
	v_lshlrev_b32_e32 v0, 11, v9
	v_lshl_add_u64 v[12:13], s[58:59], 0, v[0:1]
	v_cvt_pk_bf16_f32 v15, v16, v17
	s_waitcnt lgkmcnt(0)
	v_add_f32_e32 v0, v11, v14
	v_xor_b32_e32 v11, 2, v137
	v_cmp_lt_i32_e64 s[6:7], v11, v22
	v_cvt_pk_bf16_f32 v14, v24, v18
	s_nop 1
	v_cndmask_b32_e64 v11, v137, v11, s[6:7]
	v_lshlrev_b32_e32 v11, 2, v11
	ds_bpermute_b32 v23, v11, v0
	v_ashrrev_i32_e32 v11, 31, v10
	v_lshl_add_u64 v[12:13], v[10:11], 1, v[12:13]
	v_xor_b32_e32 v10, 4, v137
	v_cmp_lt_i32_e64 s[6:7], v10, v22
	s_waitcnt lgkmcnt(0)
	v_add_f32_e32 v0, v0, v23
	global_store_dwordx2 v[12:13], v[14:15], off sc1
	v_cndmask_b32_e64 v10, v137, v10, s[6:7]
	v_lshlrev_b32_e32 v10, 2, v10
	ds_bpermute_b32 v10, v10, v0
	v_cvt_pk_bf16_f32 v14, v25, v19
	v_cvt_pk_bf16_f32 v15, v20, v21
	global_store_dwordx2 v[12:13], v[14:15], off offset:256 sc1
	s_and_b64 exec, exec, s[0:1]
	s_cbranch_execz .LBB0_1161
	s_lshl_b32 s6, s21, 2
	s_or_b32 s6, s6, s22
	s_mul_hi_i32 s7, s6, 0x10800
	s_mul_i32 s6, s6, 0x10800
	s_add_u32 s6, s44, s6
	s_waitcnt lgkmcnt(0)
	v_add_f32_e32 v0, v0, v10
	s_addc_u32 s7, s45, s7
	v_lshlrev_b32_e32 v9, 2, v9
	global_store_dword v9, v0, s[6:7] sc1
	s_branch .LBB0_1161

.LBB0_1223:
	s_andn2_saveexec_b64 s[10:11], s[10:11]
	s_cbranch_execz .LBB0_1243
	s_mov_b64 s[10:11], exec
	s_waitcnt lgkmcnt(0)
	s_waitcnt vmcnt(0)
	buffer_inv sc1
	v_mbcnt_lo_u32_b32 v141, s10, 0
	v_mbcnt_hi_u32_b32 v141, s11, v141
	v_cmp_eq_u32_e32 vcc, 0, v141
	s_and_saveexec_b64 s[12:13], vcc
	s_cbranch_execz .LBB0_1226
	s_bcnt1_i32_b64 s3, s[10:11]
	v_mov_b32_e32 v142, 0x3000
	v_mov_b32_e32 v143, s3
	global_atomic_add v142, v142, v143, s[54:55] offset:1024 sc0

.LBB0_1387:
	s_ashr_i32 s14, s13, 6
	s_bfe_u32 s15, s13, 0x20004
	s_and_b32 s17, s3, 0x1e0
	s_lshl_b32 s8, s14, 8
	s_lshl_b32 s10, s15, 5
	s_or_b32 s16, s10, s8
	s_bitset1_b32 s17, 14
	s_waitcnt lgkmcnt(0)
	v_mad_i64_i32 v[6:7], s[10:11], s16, v18, v[4:5]
	s_mul_i32 s8, s17, 0x1600
	global_load_dwordx4 v[20:23], v[6:7], off
	v_lshl_add_u64 v[10:11], v[2:3], 0, s[8:9]
	v_add_co_u32_e32 v8, vcc, 0x16000, v10
	global_load_dwordx4 v[24:27], v[10:11], off
	s_nop 0
	v_addc_co_u32_e32 v9, vcc, 0, v11, vcc
	v_add_co_u32_e32 v14, vcc, 0x16000, v6
	global_load_dwordx4 v[28:31], v[10:11], off offset:64
	global_load_dwordx4 v[32:35], v[6:7], off offset:64
	v_addc_co_u32_e32 v15, vcc, 0, v7, vcc
	global_load_dwordx4 v[36:39], v[14:15], off
	global_load_dwordx4 v[44:47], v[8:9], off
	global_load_dwordx4 v[48:51], v[8:9], off offset:64
	global_load_dwordx4 v[52:55], v[14:15], off offset:64
	v_add_co_u32_e32 v12, vcc, 0xb0000, v6
	s_waitcnt vmcnt(6)
	v_mfma_f32_16x16x32_bf16 v[40:43], v[20:23], v[24:27], 0
	v_addc_co_u32_e32 v13, vcc, 0, v7, vcc
	v_add_co_u32_e32 v96, vcc, 0xc6000, v6
	s_waitcnt vmcnt(2)
	v_mfma_f32_16x16x32_bf16 v[20:23], v[20:23], v[44:47], 0
	v_addc_co_u32_e32 v97, vcc, 0, v7, vcc
	global_load_dwordx4 v[60:63], v[12:13], off
	global_load_dwordx4 v[64:67], v[14:15], off offset:640
	v_mfma_f32_16x16x32_bf16 v[40:43], v[32:35], v[28:31], v[40:43]
	s_waitcnt vmcnt(3)
	v_mfma_f32_16x16x32_bf16 v[20:23], v[32:35], v[48:51], v[20:23]
	global_load_dwordx4 v[32:35], v[96:97], off
	global_load_dwordx4 v[72:75], v[96:97], off offset:64
	v_mfma_f32_16x16x32_bf16 v[56:59], v[36:39], v[24:27], 0
	v_mfma_f32_16x16x32_bf16 v[36:39], v[36:39], v[44:47], 0
	s_waitcnt vmcnt(3)
	v_mfma_f32_16x16x32_bf16 v[68:71], v[60:63], v[24:27], 0
	v_mfma_f32_16x16x32_bf16 v[60:63], v[60:63], v[44:47], 0
	s_waitcnt vmcnt(1)
	v_mfma_f32_16x16x32_bf16 v[24:27], v[32:35], v[24:27], 0
	v_mfma_f32_16x16x32_bf16 v[32:35], v[32:35], v[44:47], 0
	v_mfma_f32_16x16x32_bf16 v[44:47], v[52:55], v[28:31], v[56:59]
	v_mfma_f32_16x16x32_bf16 v[36:39], v[52:55], v[48:51], v[36:39]
	global_load_dwordx4 v[52:55], v[12:13], off offset:64
	s_nop 0
	global_load_dwordx4 v[56:59], v[12:13], off offset:128
	global_load_dwordx4 v[76:79], v[6:7], off offset:128
	s_waitcnt vmcnt(3)
	v_mfma_f32_16x16x32_bf16 v[24:27], v[72:75], v[28:31], v[24:27]
	s_waitcnt vmcnt(2)
	v_mfma_f32_16x16x32_bf16 v[68:71], v[52:55], v[28:31], v[68:71]
	v_mfma_f32_16x16x32_bf16 v[52:55], v[52:55], v[48:51], v[60:63]
	s_nop 2
	global_load_dwordx4 v[60:63], v[10:11], off offset:128
	global_load_dwordx4 v[80:83], v[10:11], off offset:192
	global_load_dwordx4 v[84:87], v[6:7], off offset:192
	global_load_dwordx4 v[88:91], v[8:9], off offset:128
	global_load_dwordx4 v[92:95], v[8:9], off offset:192
	v_mfma_f32_16x16x32_bf16 v[28:31], v[72:75], v[48:51], v[32:35]
	s_nop 2
	global_load_dwordx4 v[32:35], v[14:15], off offset:128
	global_load_dwordx4 v[48:51], v[14:15], off offset:192
	s_waitcnt vmcnt(6)
	v_mfma_f32_16x16x32_bf16 v[40:43], v[76:79], v[60:63], v[40:43]
	s_waitcnt vmcnt(1)
	v_mfma_f32_16x16x32_bf16 v[44:47], v[32:35], v[60:63], v[44:47]
	v_mfma_f32_16x16x32_bf16 v[32:35], v[32:35], v[88:91], v[36:39]
	v_mfma_f32_16x16x32_bf16 v[36:39], v[56:59], v[60:63], v[68:71]
	v_mfma_f32_16x16x32_bf16 v[52:55], v[56:59], v[88:91], v[52:55]
	global_load_dwordx4 v[56:59], v[96:97], off offset:128
	s_nop 0
	global_load_dwordx4 v[68:71], v[96:97], off offset:192
	s_waitcnt vmcnt(2)
	v_mfma_f32_16x16x32_bf16 v[44:47], v[48:51], v[80:83], v[44:47]
	v_mfma_f32_16x16x32_bf16 v[32:35], v[48:51], v[92:95], v[32:35]
	v_mfma_f32_16x16x32_bf16 v[20:23], v[76:79], v[88:91], v[20:23]
	v_mfma_f32_16x16x32_bf16 v[40:43], v[84:87], v[80:83], v[40:43]
	v_mfma_f32_16x16x32_bf16 v[20:23], v[84:87], v[92:95], v[20:23]
	s_waitcnt vmcnt(1)
	v_mfma_f32_16x16x32_bf16 v[24:27], v[56:59], v[60:63], v[24:27]
	v_mfma_f32_16x16x32_bf16 v[28:31], v[56:59], v[88:91], v[28:31]
	global_load_dwordx4 v[48:51], v[12:13], off offset:192
	global_load_dwordx4 v[56:59], v[12:13], off offset:256
	s_waitcnt vmcnt(2)
	v_mfma_f32_16x16x32_bf16 v[24:27], v[68:71], v[80:83], v[24:27]
	v_mfma_f32_16x16x32_bf16 v[28:31], v[68:71], v[92:95], v[28:31]
	s_waitcnt vmcnt(1)
	v_mfma_f32_16x16x32_bf16 v[36:39], v[48:51], v[80:83], v[36:39]
	v_mfma_f32_16x16x32_bf16 v[48:51], v[48:51], v[92:95], v[52:55]
	s_nop 2
	global_load_dwordx4 v[52:55], v[6:7], off offset:256
	global_load_dwordx4 v[60:63], v[10:11], off offset:256
	global_load_dwordx4 v[68:71], v[10:11], off offset:320
	global_load_dwordx4 v[72:75], v[6:7], off offset:320
	global_load_dwordx4 v[76:79], v[8:9], off offset:256
	global_load_dwordx4 v[80:83], v[8:9], off offset:320
	s_waitcnt vmcnt(4)
	v_mfma_f32_16x16x32_bf16 v[36:39], v[56:59], v[60:63], v[36:39]
	v_mfma_f32_16x16x32_bf16 v[40:43], v[52:55], v[60:63], v[40:43]
	s_waitcnt vmcnt(1)
	v_mfma_f32_16x16x32_bf16 v[20:23], v[52:55], v[76:79], v[20:23]
	global_load_dwordx4 v[52:55], v[14:15], off offset:256
	global_load_dwordx4 v[84:87], v[14:15], off offset:320
	v_mfma_f32_16x16x32_bf16 v[48:51], v[56:59], v[76:79], v[48:51]
	s_waitcnt vmcnt(1)
	v_mfma_f32_16x16x32_bf16 v[44:47], v[52:55], v[60:63], v[44:47]
	v_mfma_f32_16x16x32_bf16 v[32:35], v[52:55], v[76:79], v[32:35]
	global_load_dwordx4 v[52:55], v[96:97], off offset:256
	global_load_dwordx4 v[56:59], v[96:97], off offset:320
	s_waitcnt vmcnt(1)
	v_mfma_f32_16x16x32_bf16 v[24:27], v[52:55], v[60:63], v[24:27]
	v_mfma_f32_16x16x32_bf16 v[28:31], v[52:55], v[76:79], v[28:31]
	global_load_dwordx4 v[52:55], v[12:13], off offset:320
	global_load_dwordx4 v[60:63], v[12:13], off offset:384
	s_waitcnt vmcnt(1)
	v_mfma_f32_16x16x32_bf16 v[36:39], v[52:55], v[68:71], v[36:39]
	v_mfma_f32_16x16x32_bf16 v[48:51], v[52:55], v[80:83], v[48:51]
	global_load_dwordx4 v[52:55], v[6:7], off offset:384
	v_mfma_f32_16x16x32_bf16 v[40:43], v[72:75], v[68:71], v[40:43]
	v_mfma_f32_16x16x32_bf16 v[20:23], v[72:75], v[80:83], v[20:23]
	v_mfma_f32_16x16x32_bf16 v[44:47], v[84:87], v[68:71], v[44:47]
	v_mfma_f32_16x16x32_bf16 v[32:35], v[84:87], v[80:83], v[32:35]
	v_mfma_f32_16x16x32_bf16 v[24:27], v[56:59], v[68:71], v[24:27]
	v_mfma_f32_16x16x32_bf16 v[28:31], v[56:59], v[80:83], v[28:31]
	global_load_dwordx4 v[56:59], v[10:11], off offset:384
	global_load_dwordx4 v[68:71], v[10:11], off offset:448
	global_load_dwordx4 v[72:75], v[6:7], off offset:448
	global_load_dwordx4 v[76:79], v[8:9], off offset:384
	global_load_dwordx4 v[80:83], v[8:9], off offset:448
	s_waitcnt vmcnt(4)
	v_mfma_f32_16x16x32_bf16 v[40:43], v[52:55], v[56:59], v[40:43]
	s_waitcnt vmcnt(1)
	v_mfma_f32_16x16x32_bf16 v[20:23], v[52:55], v[76:79], v[20:23]
	global_load_dwordx4 v[52:55], v[14:15], off offset:384
	global_load_dwordx4 v[84:87], v[14:15], off offset:448
	s_waitcnt vmcnt(1)
	v_mfma_f32_16x16x32_bf16 v[44:47], v[52:55], v[56:59], v[44:47]
	v_mfma_f32_16x16x32_bf16 v[32:35], v[52:55], v[76:79], v[32:35]
	v_mfma_f32_16x16x32_bf16 v[36:39], v[60:63], v[56:59], v[36:39]
	v_mfma_f32_16x16x32_bf16 v[48:51], v[60:63], v[76:79], v[48:51]
	global_load_dwordx4 v[52:55], v[96:97], off offset:384
	global_load_dwordx4 v[60:63], v[96:97], off offset:448
	s_waitcnt vmcnt(1)
	v_mfma_f32_16x16x32_bf16 v[24:27], v[52:55], v[56:59], v[24:27]
	v_mfma_f32_16x16x32_bf16 v[28:31], v[52:55], v[76:79], v[28:31]
	global_load_dwordx4 v[52:55], v[12:13], off offset:448
	global_load_dwordx4 v[56:59], v[12:13], off offset:512
	s_waitcnt vmcnt(1)
	v_mfma_f32_16x16x32_bf16 v[36:39], v[52:55], v[68:71], v[36:39]
	v_mfma_f32_16x16x32_bf16 v[48:51], v[52:55], v[80:83], v[48:51]
	global_load_dwordx4 v[52:55], v[6:7], off offset:512
	v_mfma_f32_16x16x32_bf16 v[40:43], v[72:75], v[68:71], v[40:43]
	v_mfma_f32_16x16x32_bf16 v[20:23], v[72:75], v[80:83], v[20:23]
	v_mfma_f32_16x16x32_bf16 v[44:47], v[84:87], v[68:71], v[44:47]
	v_mfma_f32_16x16x32_bf16 v[32:35], v[84:87], v[80:83], v[32:35]
	v_mfma_f32_16x16x32_bf16 v[24:27], v[60:63], v[68:71], v[24:27]
	v_mfma_f32_16x16x32_bf16 v[28:31], v[60:63], v[80:83], v[28:31]
	global_load_dwordx4 v[60:63], v[10:11], off offset:512
	global_load_dwordx4 v[68:71], v[10:11], off offset:576
	global_load_dwordx4 v[72:75], v[6:7], off offset:576
	global_load_dwordx4 v[76:79], v[8:9], off offset:512
	global_load_dwordx4 v[80:83], v[8:9], off offset:576
	s_waitcnt vmcnt(4)
	v_mfma_f32_16x16x32_bf16 v[40:43], v[52:55], v[60:63], v[40:43]
	s_waitcnt vmcnt(1)
	v_mfma_f32_16x16x32_bf16 v[20:23], v[52:55], v[76:79], v[20:23]
	global_load_dwordx4 v[52:55], v[14:15], off offset:512
	global_load_dwordx4 v[84:87], v[14:15], off offset:576
	s_waitcnt vmcnt(1)
	v_mfma_f32_16x16x32_bf16 v[44:47], v[52:55], v[60:63], v[44:47]
	v_mfma_f32_16x16x32_bf16 v[32:35], v[52:55], v[76:79], v[32:35]
	v_mfma_f32_16x16x32_bf16 v[36:39], v[56:59], v[60:63], v[36:39]
	v_mfma_f32_16x16x32_bf16 v[48:51], v[56:59], v[76:79], v[48:51]
	global_load_dwordx4 v[52:55], v[96:97], off offset:512
	global_load_dwordx4 v[56:59], v[96:97], off offset:576
	s_waitcnt vmcnt(1)
	v_mfma_f32_16x16x32_bf16 v[24:27], v[52:55], v[60:63], v[24:27]
	v_mfma_f32_16x16x32_bf16 v[28:31], v[52:55], v[76:79], v[28:31]
	global_load_dwordx4 v[52:55], v[12:13], off offset:576
	global_load_dwordx4 v[60:63], v[12:13], off offset:640
	s_waitcnt vmcnt(1)
	v_mfma_f32_16x16x32_bf16 v[12:15], v[52:55], v[68:71], v[36:39]
	v_mfma_f32_16x16x32_bf16 v[36:39], v[52:55], v[80:83], v[48:51]
	global_load_dwordx4 v[52:55], v[10:11], off offset:640
	s_nop 1
	global_load_dwordx4 v[48:51], v[6:7], off offset:640
	v_mfma_f32_16x16x32_bf16 v[40:43], v[72:75], v[68:71], v[40:43]
	global_load_dwordx4 v[6:9], v[8:9], off offset:640
	v_mfma_f32_16x16x32_bf16 v[20:23], v[72:75], v[80:83], v[20:23]
	s_waitcnt vmcnt(1)
	v_mfma_f32_16x16x32_bf16 v[40:43], v[48:51], v[52:55], v[40:43]
	s_waitcnt vmcnt(0)
	v_mfma_f32_16x16x32_bf16 v[20:23], v[48:51], v[6:9], v[20:23]
	global_load_dwordx4 v[48:51], v[96:97], off offset:640
	s_barrier
	v_mfma_f32_16x16x32_bf16 v[44:47], v[84:87], v[68:71], v[44:47]
	s_nop 2
	ds_write2st64_b32 v19, v40, v41 offset1:1
	ds_write2st64_b32 v19, v42, v43 offset0:2 offset1:3
	v_mfma_f32_16x16x32_bf16 v[24:27], v[56:59], v[68:71], v[24:27]
	v_mfma_f32_16x16x32_bf16 v[32:35], v[84:87], v[80:83], v[32:35]
	v_mfma_f32_16x16x32_bf16 v[44:47], v[64:67], v[52:55], v[44:47]
	v_mfma_f32_16x16x32_bf16 v[10:13], v[60:63], v[52:55], v[12:15]
	s_nop 6
	ds_write2st64_b32 v19, v44, v45 offset0:4 offset1:5
	ds_write2st64_b32 v19, v46, v47 offset0:6 offset1:7
	ds_write2st64_b32 v19, v10, v11 offset0:8 offset1:9
	s_waitcnt vmcnt(0)
	v_mfma_f32_16x16x32_bf16 v[24:27], v[48:51], v[52:55], v[24:27]
	ds_write2st64_b32 v19, v12, v13 offset0:10 offset1:11
	s_nop 6
	ds_write2st64_b32 v19, v24, v25 offset0:12 offset1:13
	ds_write2st64_b32 v19, v26, v27 offset0:14 offset1:15
	v_mfma_f32_16x16x32_bf16 v[28:31], v[56:59], v[80:83], v[28:31]
	v_mfma_f32_16x16x32_bf16 v[10:13], v[64:67], v[6:9], v[32:35]
	ds_write2st64_b32 v19, v20, v21 offset0:16 offset1:17
	ds_write2st64_b32 v19, v22, v23 offset0:18 offset1:19
	s_nop 5
	ds_write2st64_b32 v19, v10, v11 offset0:20 offset1:21
	v_mfma_f32_16x16x32_bf16 v[20:23], v[60:63], v[6:9], v[36:39]
	ds_write2st64_b32 v19, v12, v13 offset0:22 offset1:23
	s_nop 6
	ds_write2st64_b32 v19, v20, v21 offset0:24 offset1:25
	ds_write2st64_b32 v19, v22, v23 offset0:26 offset1:27
	v_mfma_f32_16x16x32_bf16 v[6:9], v[48:51], v[6:9], v[28:31]
	s_nop 7
	ds_write2st64_b32 v19, v6, v7 offset0:28 offset1:29
	ds_write2st64_b32 v19, v8, v9 offset0:30 offset1:31
	s_waitcnt lgkmcnt(0)
	s_barrier
	s_and_saveexec_b64 s[10:11], s[0:1]
	s_cbranch_execz .LBB0_1386
	ds_read2st64_b32 v[6:7], v16 offset1:1
	ds_read2st64_b32 v[8:9], v16 offset0:8 offset1:9
	ds_read2st64_b32 v[10:11], v16 offset0:10 offset1:11
	ds_read2st64_b32 v[12:13], v16 offset0:2 offset1:3
	s_waitcnt lgkmcnt(3)
	v_add_f32_e32 v0, 0, v6
	s_waitcnt lgkmcnt(2)
	v_add_f32_e32 v14, 0, v8
	v_add_f32_e32 v15, 0, v7
	v_add_f32_e32 v20, 0, v9
	ds_read2st64_b32 v[6:7], v16 offset0:32 offset1:33
	ds_read2st64_b32 v[8:9], v16 offset0:40 offset1:41
	s_waitcnt lgkmcnt(2)
	v_add_f32_e32 v21, 0, v12
	v_add_f32_e32 v22, 0, v10
	v_add_f32_e32 v23, 0, v13
	v_add_f32_e32 v24, 0, v11
	ds_read2st64_b32 v[10:11], v16 offset0:42 offset1:43
	ds_read2st64_b32 v[12:13], v16 offset0:34 offset1:35
	s_waitcnt lgkmcnt(3)
	v_add_f32_e32 v0, v0, v6
	s_waitcnt lgkmcnt(2)
	v_add_f32_e32 v14, v14, v8
	v_add_f32_e32 v15, v15, v7
	v_add_f32_e32 v20, v20, v9
	ds_read2st64_b32 v[6:7], v16 offset0:64 offset1:65
	ds_read2st64_b32 v[8:9], v16 offset0:72 offset1:73
	s_waitcnt lgkmcnt(2)
	v_add_f32_e32 v21, v21, v12
	v_add_f32_e32 v22, v22, v10
	v_add_f32_e32 v23, v23, v13
	v_add_f32_e32 v24, v24, v11
	ds_read2st64_b32 v[10:11], v16 offset0:74 offset1:75
	ds_read2st64_b32 v[12:13], v16 offset0:66 offset1:67
	s_waitcnt lgkmcnt(3)
	v_add_f32_e32 v0, v0, v6
	s_waitcnt lgkmcnt(2)
	v_add_f32_e32 v14, v14, v8
	v_add_f32_e32 v15, v15, v7
	v_add_f32_e32 v20, v20, v9
	ds_read2st64_b32 v[6:7], v16 offset0:96 offset1:97
	ds_read2st64_b32 v[8:9], v16 offset0:104 offset1:105
	s_waitcnt lgkmcnt(2)
	v_add_f32_e32 v21, v21, v12
	v_add_f32_e32 v22, v22, v10
	v_add_f32_e32 v23, v23, v13
	v_add_f32_e32 v24, v24, v11
	ds_read2st64_b32 v[10:11], v16 offset0:106 offset1:107
	ds_read2st64_b32 v[12:13], v16 offset0:98 offset1:99
	s_waitcnt lgkmcnt(3)
	v_add_f32_e32 v0, v0, v6
	s_waitcnt lgkmcnt(2)
	v_add_f32_e32 v14, v14, v8
	v_add_f32_e32 v15, v15, v7
	v_add_f32_e32 v20, v20, v9
	ds_read2st64_b32 v[6:7], v16 offset0:128 offset1:129
	ds_read2st64_b32 v[8:9], v16 offset0:136 offset1:137
	s_waitcnt lgkmcnt(2)
	v_add_f32_e32 v21, v21, v12
	v_add_f32_e32 v22, v22, v10
	v_add_f32_e32 v23, v23, v13
	v_add_f32_e32 v24, v24, v11
	ds_read2st64_b32 v[10:11], v16 offset0:138 offset1:139
	ds_read2st64_b32 v[12:13], v16 offset0:130 offset1:131
	s_waitcnt lgkmcnt(3)
	v_add_f32_e32 v0, v0, v6
	s_waitcnt lgkmcnt(2)
	v_add_f32_e32 v14, v14, v8
	v_add_f32_e32 v15, v15, v7
	v_add_f32_e32 v20, v20, v9
	ds_read2st64_b32 v[6:7], v16 offset0:160 offset1:161
	ds_read2st64_b32 v[8:9], v16 offset0:168 offset1:169
	s_waitcnt lgkmcnt(2)
	v_add_f32_e32 v21, v21, v12
	v_add_f32_e32 v22, v22, v10
	v_add_f32_e32 v23, v23, v13
	v_add_f32_e32 v24, v24, v11
	ds_read2st64_b32 v[10:11], v16 offset0:170 offset1:171
	ds_read2st64_b32 v[12:13], v16 offset0:162 offset1:163
	s_waitcnt lgkmcnt(3)
	v_add_f32_e32 v0, v0, v6
	s_waitcnt lgkmcnt(2)
	v_add_f32_e32 v14, v14, v8
	v_add_f32_e32 v15, v15, v7
	v_add_f32_e32 v20, v20, v9
	ds_read2st64_b32 v[6:7], v16 offset0:192 offset1:193
	ds_read2st64_b32 v[8:9], v16 offset0:200 offset1:201
	s_waitcnt lgkmcnt(2)
	v_add_f32_e32 v21, v21, v12
	v_add_f32_e32 v22, v22, v10
	v_add_f32_e32 v23, v23, v13
	v_add_f32_e32 v24, v24, v11
	ds_read2st64_b32 v[10:11], v16 offset0:202 offset1:203
	ds_read2st64_b32 v[12:13], v16 offset0:194 offset1:195
	s_waitcnt lgkmcnt(3)
	v_add_f32_e32 v0, v0, v6
	s_waitcnt lgkmcnt(2)
	v_add_f32_e32 v14, v14, v8
	v_add_f32_e32 v15, v15, v7
	v_add_f32_e32 v20, v20, v9
	ds_read2st64_b32 v[6:7], v16 offset0:224 offset1:225
	ds_read2st64_b32 v[8:9], v16 offset0:232 offset1:233
	s_waitcnt lgkmcnt(2)
	v_add_f32_e32 v21, v21, v12
	v_add_f32_e32 v22, v22, v10
	v_add_f32_e32 v23, v23, v13
	v_add_f32_e32 v24, v24, v11
	ds_read2st64_b32 v[10:11], v16 offset0:234 offset1:235
	ds_read2st64_b32 v[12:13], v16 offset0:226 offset1:227
	s_waitcnt lgkmcnt(3)
	v_add_f32_e32 v7, v15, v7
	s_waitcnt lgkmcnt(2)
	v_add_f32_e32 v15, v20, v9
	v_add_f32_e32 v25, v0, v6
	v_add_f32_e32 v14, v14, v8
	v_mul_f32_e32 v0, v7, v7
	v_mul_f32_e32 v6, v15, v15
	s_waitcnt lgkmcnt(0)
	v_add_f32_e32 v12, v21, v12
	v_add_f32_e32 v20, v22, v10
	v_fmac_f32_e32 v0, v25, v25
	v_fmac_f32_e32 v6, v14, v14
	v_add_f32_e32 v13, v23, v13
	v_add_f32_e32 v21, v24, v11
	v_fmac_f32_e32 v0, v12, v12
	v_fmac_f32_e32 v6, v20, v20
	v_fmac_f32_e32 v0, v13, v13
	v_fmac_f32_e32 v6, v21, v21
	v_add_f32_e32 v9, v0, v6
	v_and_b32_e32 v6, 64, v137
	v_xor_b32_e32 v0, 1, v137
	v_add_u32_e32 v22, 64, v6
	v_cmp_lt_i32_e32 vcc, v0, v22
	v_or_b32_e32 v6, s17, v182
	v_or_b32_e32 v8, s16, v17
	v_cndmask_b32_e32 v0, v137, v0, vcc
	v_lshlrev_b32_e32 v0, 2, v0
	ds_bpermute_b32 v23, v0, v9
	v_lshlrev_b32_e32 v0, 11, v6
	v_lshl_add_u64 v[10:11], s[58:59], 0, v[0:1]
	s_waitcnt lgkmcnt(0)
	v_add_f32_e32 v0, v9, v23
	v_xor_b32_e32 v9, 2, v137
	v_cmp_lt_i32_e32 vcc, v9, v22
	s_nop 1
	v_cndmask_b32_e32 v9, v137, v9, vcc
	v_lshlrev_b32_e32 v9, 2, v9
	ds_bpermute_b32 v23, v9, v0
	v_ashrrev_i32_e32 v9, 31, v8
	v_lshl_add_u64 v[8:9], v[8:9], 1, v[10:11]
	v_cvt_pk_bf16_f32 v10, v25, v7
	v_xor_b32_e32 v7, 4, v137
	v_cmp_lt_i32_e32 vcc, v7, v22
	s_waitcnt lgkmcnt(0)
	v_add_f32_e32 v0, v0, v23
	v_cvt_pk_bf16_f32 v11, v12, v13
	global_store_dwordx2 v[8:9], v[10:11], off sc1
	v_cndmask_b32_e32 v7, v137, v7, vcc
	v_lshlrev_b32_e32 v7, 2, v7
	ds_bpermute_b32 v7, v7, v0
	v_cvt_pk_bf16_f32 v10, v14, v15
	v_cvt_pk_bf16_f32 v11, v20, v21
	global_store_dwordx2 v[8:9], v[10:11], off offset:256 sc1
	s_and_b64 exec, exec, s[4:5]
	s_cbranch_execz .LBB0_1386
	s_lshl_b32 s8, s14, 2
	s_or_b32 s8, s8, s15
	s_mul_hi_i32 s15, s8, 0x10800
	s_mul_i32 s8, s8, 0x10800
	s_add_u32 s14, s44, s8
	s_waitcnt lgkmcnt(0)
	v_add_f32_e32 v0, v0, v7
	s_addc_u32 s15, s45, s15
	v_lshlrev_b32_e32 v6, 2, v6
	global_store_dword v6, v0, s[14:15] sc1
	s_branch .LBB0_1386

.LBB0_1400:
	s_nop 7
	v_xor_b32_e32 v138, 16, v137
	v_xor_b32_e32 v139, 32, v137
	v_lshlrev_b32_e32 v138, 2, v138
	v_lshlrev_b32_e32 v139, 2, v139
	v_mul_f32_e32 v140, v124, v124
	v_mul_f32_e32 v141, v108, v108
	v_mul_f32_e32 v142, v92, v92
	v_mul_f32_e32 v143, v76, v76
	v_mul_f32_e32 v144, v60, v60
	v_mul_f32_e32 v145, v44, v44
	v_mul_f32_e32 v146, v28, v28
	v_mul_f32_e32 v147, v12, v12
	v_fmac_f32_e32 v140, v125, v125
	v_fmac_f32_e32 v141, v109, v109
	v_fmac_f32_e32 v142, v93, v93
	v_fmac_f32_e32 v143, v77, v77
	v_fmac_f32_e32 v144, v61, v61
	v_fmac_f32_e32 v145, v45, v45
	v_fmac_f32_e32 v146, v29, v29
	v_fmac_f32_e32 v147, v13, v13
	v_fmac_f32_e32 v140, v126, v126
	v_fmac_f32_e32 v141, v110, v110
	v_fmac_f32_e32 v142, v94, v94
	v_fmac_f32_e32 v143, v78, v78
	v_fmac_f32_e32 v144, v62, v62
	v_fmac_f32_e32 v145, v46, v46
	v_fmac_f32_e32 v146, v30, v30
	v_fmac_f32_e32 v147, v14, v14
	v_fmac_f32_e32 v140, v127, v127
	v_fmac_f32_e32 v141, v111, v111
	v_fmac_f32_e32 v142, v95, v95
	v_fmac_f32_e32 v143, v79, v79
	v_fmac_f32_e32 v144, v63, v63
	v_fmac_f32_e32 v145, v47, v47
	v_fmac_f32_e32 v146, v31, v31
	v_fmac_f32_e32 v147, v15, v15
	v_fmac_f32_e32 v140, v112, v112
	v_fmac_f32_e32 v141, v96, v96
	v_fmac_f32_e32 v142, v80, v80
	v_fmac_f32_e32 v143, v64, v64
	v_fmac_f32_e32 v144, v48, v48
	v_fmac_f32_e32 v145, v32, v32
	v_fmac_f32_e32 v146, v16, v16
	v_fmac_f32_e32 v147, v0, v0
	v_fmac_f32_e32 v140, v113, v113
	v_fmac_f32_e32 v141, v97, v97
	v_fmac_f32_e32 v142, v81, v81
	v_fmac_f32_e32 v143, v65, v65
	v_fmac_f32_e32 v144, v49, v49
	v_fmac_f32_e32 v145, v33, v33
	v_fmac_f32_e32 v146, v17, v17
	v_fmac_f32_e32 v147, v1, v1
	v_fmac_f32_e32 v140, v114, v114
	v_fmac_f32_e32 v141, v98, v98
	v_fmac_f32_e32 v142, v82, v82
	v_fmac_f32_e32 v143, v66, v66
	v_fmac_f32_e32 v144, v50, v50
	v_fmac_f32_e32 v145, v34, v34
	v_fmac_f32_e32 v146, v18, v18
	v_fmac_f32_e32 v147, v2, v2
	v_fmac_f32_e32 v140, v115, v115
	v_fmac_f32_e32 v141, v99, v99
	v_fmac_f32_e32 v142, v83, v83
	v_fmac_f32_e32 v143, v67, v67
	v_fmac_f32_e32 v144, v51, v51
	v_fmac_f32_e32 v145, v35, v35
	v_fmac_f32_e32 v146, v19, v19
	v_fmac_f32_e32 v147, v3, v3
	v_fmac_f32_e32 v140, v120, v120
	v_fmac_f32_e32 v141, v100, v100
	v_fmac_f32_e32 v142, v84, v84
	v_fmac_f32_e32 v143, v68, v68
	v_fmac_f32_e32 v144, v52, v52
	v_fmac_f32_e32 v145, v36, v36
	v_fmac_f32_e32 v146, v20, v20
	v_fmac_f32_e32 v147, v4, v4
	v_fmac_f32_e32 v140, v121, v121
	v_fmac_f32_e32 v141, v101, v101
	v_fmac_f32_e32 v142, v85, v85
	v_fmac_f32_e32 v143, v69, v69
	v_fmac_f32_e32 v144, v53, v53
	v_fmac_f32_e32 v145, v37, v37
	v_fmac_f32_e32 v146, v21, v21
	v_fmac_f32_e32 v147, v5, v5
	v_fmac_f32_e32 v140, v122, v122
	v_fmac_f32_e32 v141, v102, v102
	v_fmac_f32_e32 v142, v86, v86
	v_fmac_f32_e32 v143, v70, v70
	v_fmac_f32_e32 v144, v54, v54
	v_fmac_f32_e32 v145, v38, v38
	v_fmac_f32_e32 v146, v22, v22
	v_fmac_f32_e32 v147, v6, v6
	v_fmac_f32_e32 v140, v123, v123
	v_fmac_f32_e32 v141, v103, v103
	v_fmac_f32_e32 v142, v87, v87
	v_fmac_f32_e32 v143, v71, v71
	v_fmac_f32_e32 v144, v55, v55
	v_fmac_f32_e32 v145, v39, v39
	v_fmac_f32_e32 v146, v23, v23
	v_fmac_f32_e32 v147, v7, v7
	v_fmac_f32_e32 v140, v116, v116
	v_fmac_f32_e32 v141, v104, v104
	v_fmac_f32_e32 v142, v88, v88
	v_fmac_f32_e32 v143, v72, v72
	v_fmac_f32_e32 v144, v56, v56
	v_fmac_f32_e32 v145, v40, v40
	v_fmac_f32_e32 v146, v24, v24
	v_fmac_f32_e32 v147, v8, v8
	v_fmac_f32_e32 v140, v117, v117
	v_fmac_f32_e32 v141, v105, v105
	v_fmac_f32_e32 v142, v89, v89
	v_fmac_f32_e32 v143, v73, v73
	v_fmac_f32_e32 v144, v57, v57
	v_fmac_f32_e32 v145, v41, v41
	v_fmac_f32_e32 v146, v25, v25
	v_fmac_f32_e32 v147, v9, v9
	v_fmac_f32_e32 v140, v118, v118
	v_fmac_f32_e32 v141, v106, v106
	v_fmac_f32_e32 v142, v90, v90
	v_fmac_f32_e32 v143, v74, v74
	v_fmac_f32_e32 v144, v58, v58
	v_fmac_f32_e32 v145, v42, v42
	v_fmac_f32_e32 v146, v26, v26
	v_fmac_f32_e32 v147, v10, v10
	v_fmac_f32_e32 v140, v119, v119
	v_fmac_f32_e32 v141, v107, v107
	v_fmac_f32_e32 v142, v91, v91
	v_fmac_f32_e32 v143, v75, v75
	v_fmac_f32_e32 v144, v59, v59
	v_fmac_f32_e32 v145, v43, v43
	v_fmac_f32_e32 v146, v27, v27
	v_fmac_f32_e32 v147, v11, v11
	ds_bpermute_b32 v148, v138, v140
	ds_bpermute_b32 v149, v138, v141
	ds_bpermute_b32 v150, v138, v142
	ds_bpermute_b32 v151, v138, v143
	ds_bpermute_b32 v152, v138, v144
	ds_bpermute_b32 v153, v138, v145
	ds_bpermute_b32 v154, v138, v146
	ds_bpermute_b32 v155, v138, v147
	s_waitcnt lgkmcnt(0)
	v_add_f32_e32 v140, v140, v148
	v_add_f32_e32 v141, v141, v149
	v_add_f32_e32 v142, v142, v150
	v_add_f32_e32 v143, v143, v151
	v_add_f32_e32 v144, v144, v152
	v_add_f32_e32 v145, v145, v153
	v_add_f32_e32 v146, v146, v154
	v_add_f32_e32 v147, v147, v155
	ds_bpermute_b32 v148, v139, v140
	ds_bpermute_b32 v149, v139, v141
	ds_bpermute_b32 v150, v139, v142
	ds_bpermute_b32 v151, v139, v143
	ds_bpermute_b32 v152, v139, v144
	ds_bpermute_b32 v153, v139, v145
	ds_bpermute_b32 v154, v139, v146
	ds_bpermute_b32 v155, v139, v147
	s_waitcnt lgkmcnt(0)
	v_add_f32_e32 v140, v140, v148
	v_add_f32_e32 v141, v141, v149
	v_add_f32_e32 v142, v142, v150
	v_add_f32_e32 v143, v143, v151
	v_add_f32_e32 v144, v144, v152
	v_add_f32_e32 v145, v145, v153
	v_add_f32_e32 v146, v146, v154
	v_add_f32_e32 v147, v147, v155
	v_lshrrev_b32_e32 v158, 8, v136
	v_bfe_u32 v159, v136, 6, 2
	v_and_b32_e32 v160, 15, v136
	v_lshl_add_u32 v160, v158, 6, v160
	v_mul_u32_u24_e32 v159, 0x4200, v159
	v_add_u32_e32 v160, v160, v159
	v_lshlrev_b32_e32 v160, 2, v160
	s_mul_i32 s24, s22, 0x42000
	s_lshl_b32 s25, s23, 10
	s_add_u32 s18, s44, s24
	s_addc_u32 s19, s45, 0
	s_add_u32 s18, s18, s25
	s_addc_u32 s19, s19, 0
	v_bfe_u32 v161, v136, 4, 2
	v_cmp_eq_u32_e32 vcc, 0, v161
	s_and_saveexec_b64 s[0:1], vcc
	global_store_dword v160, v140, s[18:19] sc1
	global_store_dword v160, v141, s[18:19] offset:64 sc1
	global_store_dword v160, v142, s[18:19] offset:128 sc1
	global_store_dword v160, v143, s[18:19] offset:192 sc1
	global_store_dword v160, v144, s[18:19] offset:512 sc1
	global_store_dword v160, v145, s[18:19] offset:576 sc1
	global_store_dword v160, v146, s[18:19] offset:640 sc1
	global_store_dword v160, v147, s[18:19] offset:704 sc1
	s_or_b64 exec, exec, s[0:1]
	s_branch .LBB0_1392

.LBB0_1448:
	s_andn2_saveexec_b64 s[8:9], s[8:9]
	s_cbranch_execz .LBB0_1468
	s_mov_b64 s[8:9], exec
	s_waitcnt lgkmcnt(0)
	s_waitcnt vmcnt(0)
	buffer_inv sc1
	v_mbcnt_lo_u32_b32 v141, s8, 0
	v_mbcnt_hi_u32_b32 v141, s9, v141
	v_cmp_eq_u32_e32 vcc, 0, v141
	s_and_saveexec_b64 s[10:11], vcc
	s_cbranch_execz .LBB0_1451
	s_bcnt1_i32_b64 s3, s[8:9]
	v_mov_b32_e32 v142, 0x3000
	v_mov_b32_e32 v143, s3
	global_atomic_add v142, v142, v143, s[54:55] offset:1024 sc0
